# m2 row-norm 64-lane sum butterflies: first four shuffle steps via DPP instead of ds_bpermute round trips (12 sites)
# speedup vs baseline: 1.0019x; 1.0019x over previous
.LBB0_111:
	v_add_u32_e32 v8, 8, v50
	v_cmp_gt_i32_e64 s[42:43], s13, v8
	v_add_u32_e32 v28, s96, v50
	v_ashrrev_i32_e32 v29, 31, v28
	v_cndmask_b32_e64 v8, v50, v8, s[42:43]
	v_add_u32_e32 v8, s96, v8
	v_ashrrev_i32_e32 v9, 31, v8
	v_lshlrev_b64 v[10:11], 9, v[8:9]
	v_lshlrev_b64 v[8:9], 11, v[8:9]
	v_lshl_add_u64 v[22:23], v[12:13], 0, v[10:11]
	v_lshl_add_u64 v[10:11], v[14:15], 0, v[10:11]
	v_lshl_add_u64 v[8:9], v[18:19], 0, v[8:9]
	global_load_dwordx2 v[40:41], v[22:23], off
	global_load_dwordx2 v[38:39], v[10:11], off
	global_load_dwordx2 v[36:37], v[8:9], off offset:1536
	v_add_u32_e32 v8, 16, v50
	v_cmp_gt_i32_e64 s[40:41], s13, v8
	s_nop 1
	v_cndmask_b32_e64 v8, v50, v8, s[40:41]
	v_add_u32_e32 v8, s96, v8
	v_ashrrev_i32_e32 v9, 31, v8
	v_lshlrev_b64 v[10:11], 9, v[8:9]
	v_lshlrev_b64 v[8:9], 11, v[8:9]
	v_lshl_add_u64 v[22:23], v[12:13], 0, v[10:11]
	v_lshl_add_u64 v[10:11], v[14:15], 0, v[10:11]
	v_lshl_add_u64 v[8:9], v[18:19], 0, v[8:9]
	global_load_dwordx2 v[34:35], v[22:23], off
	global_load_dwordx2 v[32:33], v[10:11], off
	global_load_dwordx2 v[30:31], v[8:9], off offset:1536
	v_add_u32_e32 v8, 24, v50
	v_cmp_gt_i32_e32 vcc, s13, v8
	s_nop 1
	v_cndmask_b32_e32 v8, v50, v8, vcc
	v_add_u32_e32 v8, s96, v8
	v_ashrrev_i32_e32 v9, 31, v8
	v_lshlrev_b64 v[10:11], 9, v[8:9]
	v_lshlrev_b64 v[8:9], 11, v[8:9]
	v_lshl_add_u64 v[22:23], v[12:13], 0, v[10:11]
	v_lshl_add_u64 v[10:11], v[14:15], 0, v[10:11]
	v_lshl_add_u64 v[8:9], v[18:19], 0, v[8:9]
	global_load_dwordx2 v[26:27], v[22:23], off
	global_load_dwordx2 v[24:25], v[10:11], off
	s_nop 0
	global_load_dwordx2 v[22:23], v[8:9], off offset:1536
	v_lshlrev_b64 v[8:9], 11, v[28:29]
	v_lshl_add_u64 v[42:43], v[18:19], 0, v[8:9]
	v_lshlrev_b64 v[8:9], 9, v[28:29]
	v_lshl_add_u64 v[10:11], v[14:15], 0, v[8:9]
	v_lshl_add_u64 v[8:9], v[12:13], 0, v[8:9]
	global_load_dwordx2 v[44:45], v[42:43], off offset:1536
	s_nop 0
	global_load_dwordx2 v[10:11], v[10:11], off
	s_waitcnt vmcnt(1)
	v_lshlrev_b32_e32 v52, 16, v45
	global_load_dwordx2 v[8:9], v[8:9], off
	s_waitcnt vmcnt(1)
	v_and_b32_e32 v47, 0xffff0000, v11
	v_lshlrev_b32_e32 v46, 16, v11
	v_and_b32_e32 v49, 0xffff0000, v10
	v_lshlrev_b32_e32 v48, 16, v10
	v_and_b32_e32 v53, 0xffff0000, v45
	v_mov_b32_e32 v45, v53
	s_waitcnt vmcnt(0)
	v_and_b32_e32 v11, 0xffff0000, v9
	v_lshlrev_b32_e32 v10, 16, v9
	v_pk_fma_f32 v[10:11], v[6:7], v[46:47], v[10:11]
	v_lshlrev_b32_e32 v46, 16, v44
	v_mul_f32_e32 v29, 0x3d372713, v46
	v_and_b32_e32 v47, 0xffff0000, v44
	v_mul_f32_e32 v29, v29, v46
	v_mov_b32_e32 v44, v46
	v_fmac_f32_e32 v44, v29, v44
	v_mul_f32_e32 v29, 0xbfcc422a, v44
	v_mul_f32_e32 v29, 0x3fb8aa3b, v29
	v_exp_f32_e32 v29, v29
	v_and_b32_e32 v9, 0xffff0000, v8
	v_lshlrev_b32_e32 v8, 16, v8
	v_pk_fma_f32 v[8:9], v[4:5], v[48:49], v[8:9]
	v_add_f32_e32 v29, 1.0, v29
	v_rcp_f32_e32 v48, v29
	v_mul_f32_e32 v29, 0x3d372713, v47
	v_mul_f32_e32 v29, v29, v47
	v_mov_b32_e32 v44, v47
	v_fmac_f32_e32 v44, v29, v44
	v_mul_f32_e32 v29, 0xbfcc422a, v44
	v_mul_f32_e32 v29, 0x3fb8aa3b, v29
	v_exp_f32_e32 v29, v29
	v_mov_b32_e32 v44, v52
	v_add_f32_e32 v29, 1.0, v29
	v_rcp_f32_e32 v49, v29
	v_mul_f32_e32 v29, 0x3d372713, v52
	v_mul_f32_e32 v29, v29, v52
	v_fmac_f32_e32 v44, v29, v44
	v_mul_f32_e32 v29, 0xbfcc422a, v44
	v_mul_f32_e32 v29, 0x3fb8aa3b, v29
	v_exp_f32_e32 v29, v29
	v_pk_mul_f32 v[46:47], v[48:49], v[46:47]
	v_add_f32_e32 v29, 1.0, v29
	v_rcp_f32_e32 v44, v29
	v_mul_f32_e32 v29, 0x3d372713, v53
	v_mul_f32_e32 v29, v29, v53
	v_fmac_f32_e32 v45, v29, v45
	v_mul_f32_e32 v29, 0xbfcc422a, v45
	v_mul_f32_e32 v29, 0x3fb8aa3b, v29
	v_exp_f32_e32 v29, v29
	v_pk_mul_f32 v[46:47], v[8:9], v[46:47]
	v_add_f32_e32 v29, 1.0, v29
	v_rcp_f32_e32 v45, v29
	v_pk_mul_f32 v[48:49], v[46:47], v[46:47]
	v_pk_mul_f32 v[44:45], v[44:45], v[52:53]
	s_nop 0
	v_pk_mul_f32 v[44:45], v[10:11], v[44:45]
	v_add_f32_e32 v29, v48, v49
	v_pk_mul_f32 v[52:53], v[44:45], v[44:45]
	s_nop 0
	v_add_f32_e32 v29, v52, v29
	v_add_f32_e32 v29, v53, v29
	s_nop 1
	v_mov_b32_dpp v48, v29 quad_perm:[1,0,3,2] row_mask:0xf bank_mask:0xf

	v_add_f32_e32 v29, v29, v48
	s_nop 1
	v_mov_b32_dpp v48, v29 quad_perm:[2,3,0,1] row_mask:0xf bank_mask:0xf

	v_add_f32_e32 v29, v29, v48
	s_nop 1
	v_mov_b32_dpp v48, v29 row_half_mirror row_mask:0xf bank_mask:0xf

	v_add_f32_e32 v29, v29, v48
	s_nop 1
	v_mov_b32_dpp v48, v29 row_mirror row_mask:0xf bank_mask:0xf

	v_add_f32_e32 v29, v29, v48
	ds_bpermute_b32 v48, v135, v29
	s_waitcnt lgkmcnt(0)
	v_add_f32_e32 v29, v29, v48
	ds_bpermute_b32 v48, v136, v29
	s_waitcnt lgkmcnt(0)
	v_add_f32_e32 v29, v29, v48
	v_fmamk_f32 v29, v29, 0x3b800000, v191
	v_cmp_gt_f32_e64 s[44:45], s77, v29
	v_mul_f32_e32 v48, 0x4b800000, v29
	s_nop 0
	v_cndmask_b32_e64 v29, v29, v48, s[44:45]
	v_rsq_f32_e32 v29, v29
	s_nop 0
	v_mul_f32_e32 v48, 0x45800000, v29
	v_cndmask_b32_e64 v29, v29, v48, s[44:45]
	v_cmp_eq_u32_e64 s[44:45], s24, v50
	v_mul_f32_e32 v46, v46, v29
	v_mul_f32_e32 v47, v47, v29
	s_and_b64 s[16:17], s[46:47], s[44:45]
	v_cvt_pk_bf16_f32 v46, v46, v47
	v_mul_f32_e32 v44, v44, v29
	v_mul_f32_e32 v29, v45, v29
	v_cvt_pk_bf16_f32 v47, v44, v29
	global_store_dwordx2 v[42:43], v[46:47], off offset:1536
	s_and_saveexec_b64 s[10:11], s[16:17]
	s_cbranch_execz .LBB0_113
	global_store_dwordx4 v[16:17], v[8:11], off
.LBB0_113:
	s_or_b64 exec, exec, s[10:11]
	s_and_saveexec_b64 s[10:11], s[42:43]
	s_cbranch_execz .LBB0_116
	v_lshlrev_b32_e32 v8, 16, v40
	v_and_b32_e32 v9, 0xffff0000, v40
	v_lshlrev_b32_e32 v10, 16, v41
	v_and_b32_e32 v11, 0xffff0000, v41
	v_lshlrev_b32_e32 v40, 16, v38
	v_and_b32_e32 v41, 0xffff0000, v38
	v_lshlrev_b32_e32 v38, 16, v39
	v_and_b32_e32 v39, 0xffff0000, v39
	v_pk_fma_f32 v[10:11], v[6:7], v[38:39], v[10:11]
	v_lshlrev_b32_e32 v38, 16, v36
	v_mul_f32_e32 v29, 0x3d372713, v38
	v_and_b32_e32 v39, 0xffff0000, v36
	v_mul_f32_e32 v29, v29, v38
	v_mov_b32_e32 v36, v38
	v_fmac_f32_e32 v36, v29, v36
	v_mul_f32_e32 v29, 0xbfcc422a, v36
	v_mul_f32_e32 v36, 0x3d372713, v39
	v_mul_f32_e32 v36, v36, v39
	v_mov_b32_e32 v42, v39
	v_fmac_f32_e32 v42, v36, v42
	v_mul_f32_e32 v29, 0x3fb8aa3b, v29
	v_mul_f32_e32 v36, 0xbfcc422a, v42
	v_exp_f32_e32 v29, v29
	v_mul_f32_e32 v36, 0x3fb8aa3b, v36
	v_exp_f32_e32 v42, v36
	v_pk_fma_f32 v[8:9], v[4:5], v[40:41], v[8:9]
	v_lshlrev_b32_e32 v40, 16, v37
	v_add_f32_e32 v29, 1.0, v29
	v_and_b32_e32 v41, 0xffff0000, v37
	v_mul_f32_e32 v37, 0x3d372713, v40
	v_rcp_f32_e32 v36, v29
	v_add_f32_e32 v29, 1.0, v42
	v_mul_f32_e32 v37, v37, v40
	v_mov_b32_e32 v42, v40
	v_fmac_f32_e32 v42, v37, v42
	v_mul_f32_e32 v37, 0xbfcc422a, v42
	v_mul_f32_e32 v37, 0x3fb8aa3b, v37
	v_exp_f32_e32 v42, v37
	v_mul_f32_e32 v37, 0x3d372713, v41
	v_mul_f32_e32 v37, v37, v41
	v_mov_b32_e32 v43, v41
	v_fmac_f32_e32 v43, v37, v43
	v_mul_f32_e32 v37, 0xbfcc422a, v43
	v_mul_f32_e32 v37, 0x3fb8aa3b, v37
	v_exp_f32_e32 v43, v37
	v_rcp_f32_e32 v37, v29
	v_add_f32_e32 v29, 1.0, v42
	v_rcp_f32_e32 v42, v29
	v_add_f32_e32 v29, 1.0, v43
	v_rcp_f32_e32 v43, v29
	v_pk_mul_f32 v[36:37], v[36:37], v[38:39]
	v_pk_mul_f32 v[40:41], v[42:43], v[40:41]
	v_pk_mul_f32 v[36:37], v[8:9], v[36:37]
	v_pk_mul_f32 v[40:41], v[10:11], v[40:41]
	v_pk_mul_f32 v[38:39], v[36:37], v[36:37]
	v_pk_mul_f32 v[42:43], v[40:41], v[40:41]
	v_add_f32_e32 v29, v38, v39
	v_add_f32_e32 v29, v42, v29
	v_add_f32_e32 v29, v43, v29
	s_nop 1
	v_mov_b32_dpp v38, v29 quad_perm:[1,0,3,2] row_mask:0xf bank_mask:0xf

	v_add_f32_e32 v29, v29, v38
	s_nop 1
	v_mov_b32_dpp v38, v29 quad_perm:[2,3,0,1] row_mask:0xf bank_mask:0xf

	v_add_f32_e32 v29, v29, v38
	s_nop 1
	v_mov_b32_dpp v38, v29 row_half_mirror row_mask:0xf bank_mask:0xf

	v_add_f32_e32 v29, v29, v38
	s_nop 1
	v_mov_b32_dpp v38, v29 row_mirror row_mask:0xf bank_mask:0xf

	v_add_f32_e32 v29, v29, v38
	ds_bpermute_b32 v38, v135, v29
	s_waitcnt lgkmcnt(0)
	v_add_f32_e32 v29, v29, v38
	ds_bpermute_b32 v38, v136, v29
	s_waitcnt lgkmcnt(0)
	v_add_f32_e32 v29, v29, v38
	v_fmamk_f32 v29, v29, 0x3b800000, v191
	v_mul_f32_e32 v38, 0x4b800000, v29
	v_cmp_gt_f32_e64 s[42:43], s77, v29
	s_nop 1
	v_cndmask_b32_e64 v29, v29, v38, s[42:43]
	v_rsq_f32_e32 v29, v29
	v_add_u32_e32 v38, 8, v28
	v_ashrrev_i32_e32 v39, 31, v38
	v_lshlrev_b64 v[38:39], 11, v[38:39]
	v_mul_f32_e32 v42, 0x45800000, v29
	v_cndmask_b32_e64 v29, v29, v42, s[42:43]
	v_mul_f32_e32 v36, v36, v29
	v_mul_f32_e32 v37, v37, v29
	v_cmp_eq_u32_e64 s[42:43], s33, v50
	v_cvt_pk_bf16_f32 v36, v36, v37
	v_mul_f32_e32 v37, v40, v29
	v_lshl_add_u64 v[38:39], v[18:19], 0, v[38:39]
	s_and_b64 s[16:17], s[46:47], s[42:43]
	v_mul_f32_e32 v29, v41, v29
	v_cvt_pk_bf16_f32 v37, v37, v29
	global_store_dwordx2 v[38:39], v[36:37], off offset:1536
	s_and_b64 exec, exec, s[16:17]
	s_cbranch_execz .LBB0_116
	global_store_dwordx4 v[16:17], v[8:11], off
.LBB0_116:
	s_or_b64 exec, exec, s[10:11]
	s_and_saveexec_b64 s[10:11], s[40:41]
	s_cbranch_execz .LBB0_119
	v_lshlrev_b32_e32 v8, 16, v34
	v_and_b32_e32 v9, 0xffff0000, v34
	v_lshlrev_b32_e32 v10, 16, v35
	v_and_b32_e32 v11, 0xffff0000, v35
	v_lshlrev_b32_e32 v34, 16, v32
	v_and_b32_e32 v35, 0xffff0000, v32
	v_lshlrev_b32_e32 v32, 16, v33
	v_and_b32_e32 v33, 0xffff0000, v33
	v_pk_fma_f32 v[10:11], v[6:7], v[32:33], v[10:11]
	v_lshlrev_b32_e32 v32, 16, v30
	v_mul_f32_e32 v29, 0x3d372713, v32
	v_and_b32_e32 v33, 0xffff0000, v30
	v_mul_f32_e32 v29, v29, v32
	v_mov_b32_e32 v30, v32
	v_fmac_f32_e32 v30, v29, v30
	v_mul_f32_e32 v29, 0xbfcc422a, v30
	v_mul_f32_e32 v30, 0x3d372713, v33
	v_mul_f32_e32 v30, v30, v33
	v_mov_b32_e32 v36, v33
	v_fmac_f32_e32 v36, v30, v36
	v_mul_f32_e32 v29, 0x3fb8aa3b, v29
	v_mul_f32_e32 v30, 0xbfcc422a, v36
	v_exp_f32_e32 v29, v29
	v_mul_f32_e32 v30, 0x3fb8aa3b, v30
	v_exp_f32_e32 v36, v30
	v_pk_fma_f32 v[8:9], v[4:5], v[34:35], v[8:9]
	v_lshlrev_b32_e32 v34, 16, v31
	v_add_f32_e32 v29, 1.0, v29
	v_and_b32_e32 v35, 0xffff0000, v31
	v_mul_f32_e32 v31, 0x3d372713, v34
	v_rcp_f32_e32 v30, v29
	v_add_f32_e32 v29, 1.0, v36
	v_mul_f32_e32 v31, v31, v34
	v_mov_b32_e32 v36, v34
	v_fmac_f32_e32 v36, v31, v36
	v_mul_f32_e32 v31, 0xbfcc422a, v36
	v_mul_f32_e32 v31, 0x3fb8aa3b, v31
	v_exp_f32_e32 v36, v31
	v_mul_f32_e32 v31, 0x3d372713, v35
	v_mul_f32_e32 v31, v31, v35
	v_mov_b32_e32 v37, v35
	v_fmac_f32_e32 v37, v31, v37
	v_mul_f32_e32 v31, 0xbfcc422a, v37
	v_mul_f32_e32 v31, 0x3fb8aa3b, v31
	v_exp_f32_e32 v37, v31
	v_rcp_f32_e32 v31, v29
	v_add_f32_e32 v29, 1.0, v36
	v_rcp_f32_e32 v36, v29
	v_add_f32_e32 v29, 1.0, v37
	v_rcp_f32_e32 v37, v29
	v_pk_mul_f32 v[30:31], v[30:31], v[32:33]
	v_pk_mul_f32 v[34:35], v[36:37], v[34:35]
	v_pk_mul_f32 v[30:31], v[8:9], v[30:31]
	v_pk_mul_f32 v[34:35], v[10:11], v[34:35]
	v_pk_mul_f32 v[32:33], v[30:31], v[30:31]
	v_pk_mul_f32 v[36:37], v[34:35], v[34:35]
	v_add_f32_e32 v29, v32, v33
	v_add_f32_e32 v29, v36, v29
	v_add_f32_e32 v29, v37, v29
	s_nop 1
	v_mov_b32_dpp v32, v29 quad_perm:[1,0,3,2] row_mask:0xf bank_mask:0xf

	v_add_f32_e32 v29, v29, v32
	s_nop 1
	v_mov_b32_dpp v32, v29 quad_perm:[2,3,0,1] row_mask:0xf bank_mask:0xf

	v_add_f32_e32 v29, v29, v32
	s_nop 1
	v_mov_b32_dpp v32, v29 row_half_mirror row_mask:0xf bank_mask:0xf

	v_add_f32_e32 v29, v29, v32
	s_nop 1
	v_mov_b32_dpp v32, v29 row_mirror row_mask:0xf bank_mask:0xf

	v_add_f32_e32 v29, v29, v32
	ds_bpermute_b32 v32, v135, v29
	s_waitcnt lgkmcnt(0)
	v_add_f32_e32 v29, v29, v32
	ds_bpermute_b32 v32, v136, v29
	s_waitcnt lgkmcnt(0)
	v_add_f32_e32 v29, v29, v32
	v_fmamk_f32 v29, v29, 0x3b800000, v191
	v_mul_f32_e32 v32, 0x4b800000, v29
	v_cmp_gt_f32_e64 s[40:41], s77, v29
	s_nop 1
	v_cndmask_b32_e64 v29, v29, v32, s[40:41]
	v_rsq_f32_e32 v29, v29
	v_add_u32_e32 v32, 16, v28
	v_ashrrev_i32_e32 v33, 31, v32
	v_lshlrev_b64 v[32:33], 11, v[32:33]
	v_mul_f32_e32 v36, 0x45800000, v29
	v_cndmask_b32_e64 v29, v29, v36, s[40:41]
	v_mul_f32_e32 v30, v30, v29
	v_mul_f32_e32 v31, v31, v29
	v_cmp_eq_u32_e64 s[40:41], s30, v50
	v_cvt_pk_bf16_f32 v30, v30, v31
	v_mul_f32_e32 v31, v34, v29
	v_lshl_add_u64 v[32:33], v[18:19], 0, v[32:33]
	s_and_b64 s[16:17], s[46:47], s[40:41]
	v_mul_f32_e32 v29, v35, v29
	v_cvt_pk_bf16_f32 v31, v31, v29
	global_store_dwordx2 v[32:33], v[30:31], off offset:1536
	s_and_b64 exec, exec, s[16:17]
	s_cbranch_execz .LBB0_119
	global_store_dwordx4 v[16:17], v[8:11], off
.LBB0_119:
	s_or_b64 exec, exec, s[10:11]
	s_and_saveexec_b64 s[10:11], vcc
	s_cbranch_execz .LBB0_110
	v_lshlrev_b32_e32 v8, 16, v26
	v_and_b32_e32 v9, 0xffff0000, v26
	v_lshlrev_b32_e32 v10, 16, v27
	v_and_b32_e32 v11, 0xffff0000, v27
	v_lshlrev_b32_e32 v26, 16, v24
	v_and_b32_e32 v27, 0xffff0000, v24
	v_lshlrev_b32_e32 v24, 16, v25
	v_and_b32_e32 v25, 0xffff0000, v25
	v_pk_fma_f32 v[10:11], v[6:7], v[24:25], v[10:11]
	v_lshlrev_b32_e32 v24, 16, v22
	v_and_b32_e32 v25, 0xffff0000, v22
	v_mul_f32_e32 v22, 0x3d372713, v24
	v_mul_f32_e32 v22, v22, v24
	v_mov_b32_e32 v29, v24
	v_fmac_f32_e32 v29, v22, v29
	v_mul_f32_e32 v22, 0xbfcc422a, v29
	v_mul_f32_e32 v29, 0x3d372713, v25
	v_mul_f32_e32 v29, v29, v25
	v_mov_b32_e32 v30, v25
	v_pk_fma_f32 v[8:9], v[4:5], v[26:27], v[8:9]
	v_lshlrev_b32_e32 v26, 16, v23
	v_fmac_f32_e32 v30, v29, v30
	v_and_b32_e32 v27, 0xffff0000, v23
	v_mul_f32_e32 v23, 0x3d372713, v26
	v_mul_f32_e32 v29, 0xbfcc422a, v30
	v_mul_f32_e32 v23, v23, v26
	v_mov_b32_e32 v30, v26
	v_fmac_f32_e32 v30, v23, v30
	v_mul_f32_e32 v23, 0xbfcc422a, v30
	v_mul_f32_e32 v23, 0x3fb8aa3b, v23
	v_exp_f32_e32 v30, v23
	v_mul_f32_e32 v23, 0x3d372713, v27
	v_mul_f32_e32 v23, v23, v27
	v_mov_b32_e32 v31, v27
	v_mul_f32_e32 v29, 0x3fb8aa3b, v29
	v_fmac_f32_e32 v31, v23, v31
	v_mul_f32_e32 v22, 0x3fb8aa3b, v22
	v_exp_f32_e32 v29, v29
	v_mul_f32_e32 v23, 0xbfcc422a, v31
	v_exp_f32_e32 v22, v22
	v_mul_f32_e32 v23, 0x3fb8aa3b, v23
	v_exp_f32_e32 v31, v23
	v_add_f32_e32 v29, 1.0, v29
	v_add_f32_e32 v22, 1.0, v22
	v_rcp_f32_e32 v23, v29
	v_add_f32_e32 v29, 1.0, v30
	v_rcp_f32_e32 v22, v22
	v_rcp_f32_e32 v30, v29
	v_add_f32_e32 v29, 1.0, v31
	v_rcp_f32_e32 v31, v29
	v_pk_mul_f32 v[22:23], v[22:23], v[24:25]
	v_pk_mul_f32 v[26:27], v[30:31], v[26:27]
	v_pk_mul_f32 v[22:23], v[8:9], v[22:23]
	v_pk_mul_f32 v[26:27], v[10:11], v[26:27]
	v_pk_mul_f32 v[24:25], v[22:23], v[22:23]
	v_pk_mul_f32 v[30:31], v[26:27], v[26:27]
	v_add_f32_e32 v24, v24, v25
	v_add_f32_e32 v24, v30, v24
	v_add_f32_e32 v24, v31, v24
	s_nop 1
	v_mov_b32_dpp v25, v24 quad_perm:[1,0,3,2] row_mask:0xf bank_mask:0xf

	v_add_f32_e32 v24, v24, v25
	s_nop 1
	v_mov_b32_dpp v25, v24 quad_perm:[2,3,0,1] row_mask:0xf bank_mask:0xf

	v_add_f32_e32 v24, v24, v25
	s_nop 1
	v_mov_b32_dpp v25, v24 row_half_mirror row_mask:0xf bank_mask:0xf

	v_add_f32_e32 v24, v24, v25
	s_nop 1
	v_mov_b32_dpp v25, v24 row_mirror row_mask:0xf bank_mask:0xf

	v_add_f32_e32 v24, v24, v25
	ds_bpermute_b32 v25, v135, v24
	s_waitcnt lgkmcnt(0)
	v_add_f32_e32 v24, v24, v25
	ds_bpermute_b32 v25, v136, v24
	s_waitcnt lgkmcnt(0)
	v_add_f32_e32 v24, v24, v25
	v_fmamk_f32 v24, v24, 0x3b800000, v191
	v_mul_f32_e32 v25, 0x4b800000, v24
	v_cmp_gt_f32_e32 vcc, s77, v24
	s_nop 1
	v_cndmask_b32_e32 v24, v24, v25, vcc
	v_rsq_f32_e32 v29, v24
	v_add_u32_e32 v24, 24, v28
	v_ashrrev_i32_e32 v25, 31, v24
	v_lshlrev_b64 v[24:25], 11, v[24:25]
	v_mul_f32_e32 v28, 0x45800000, v29
	v_cndmask_b32_e32 v28, v29, v28, vcc
	v_mul_f32_e32 v22, v22, v28
	v_mul_f32_e32 v23, v23, v28
	v_cmp_eq_u32_e32 vcc, s29, v50
	v_cvt_pk_bf16_f32 v22, v22, v23
	v_mul_f32_e32 v23, v26, v28
	v_lshl_add_u64 v[24:25], v[18:19], 0, v[24:25]
	s_and_b64 s[16:17], s[46:47], vcc
	v_mul_f32_e32 v26, v27, v28
	v_cvt_pk_bf16_f32 v23, v23, v26
	global_store_dwordx2 v[24:25], v[22:23], off offset:1536
	s_and_b64 exec, exec, s[16:17]
	s_cbranch_execz .LBB0_110
	global_store_dwordx4 v[16:17], v[8:11], off
	s_branch .LBB0_110

.LBB0_347:
	v_add_u32_e32 v8, 8, v56
	v_cmp_gt_i32_e64 s[42:43], s13, v8
	v_add_u32_e32 v28, s15, v56
	v_ashrrev_i32_e32 v29, 31, v28
	v_cndmask_b32_e64 v8, v56, v8, s[42:43]
	v_add_u32_e32 v8, s15, v8
	v_ashrrev_i32_e32 v9, 31, v8
	v_lshlrev_b64 v[10:11], 9, v[8:9]
	v_lshlrev_b64 v[8:9], 11, v[8:9]
	v_lshl_add_u64 v[22:23], v[12:13], 0, v[10:11]
	v_lshl_add_u64 v[10:11], v[14:15], 0, v[10:11]
	v_lshl_add_u64 v[8:9], v[18:19], 0, v[8:9]
	global_load_dwordx2 v[40:41], v[22:23], off
	global_load_dwordx2 v[38:39], v[10:11], off
	global_load_dwordx2 v[36:37], v[8:9], off offset:1536
	v_add_u32_e32 v8, 16, v56
	v_cmp_gt_i32_e64 s[40:41], s13, v8
	s_nop 1
	v_cndmask_b32_e64 v8, v56, v8, s[40:41]
	v_add_u32_e32 v8, s15, v8
	v_ashrrev_i32_e32 v9, 31, v8
	v_lshlrev_b64 v[10:11], 9, v[8:9]
	v_lshlrev_b64 v[8:9], 11, v[8:9]
	v_lshl_add_u64 v[22:23], v[12:13], 0, v[10:11]
	v_lshl_add_u64 v[10:11], v[14:15], 0, v[10:11]
	v_lshl_add_u64 v[8:9], v[18:19], 0, v[8:9]
	global_load_dwordx2 v[34:35], v[22:23], off
	global_load_dwordx2 v[32:33], v[10:11], off
	global_load_dwordx2 v[30:31], v[8:9], off offset:1536
	v_add_u32_e32 v8, 24, v56
	v_cmp_gt_i32_e32 vcc, s13, v8
	s_nop 1
	v_cndmask_b32_e32 v8, v56, v8, vcc
	v_add_u32_e32 v8, s15, v8
	v_ashrrev_i32_e32 v9, 31, v8
	v_lshlrev_b64 v[10:11], 9, v[8:9]
	v_lshlrev_b64 v[8:9], 11, v[8:9]
	v_lshl_add_u64 v[22:23], v[12:13], 0, v[10:11]
	v_lshl_add_u64 v[10:11], v[14:15], 0, v[10:11]
	v_lshl_add_u64 v[8:9], v[18:19], 0, v[8:9]
	global_load_dwordx2 v[26:27], v[22:23], off
	global_load_dwordx2 v[24:25], v[10:11], off
	s_nop 0
	global_load_dwordx2 v[22:23], v[8:9], off offset:1536
	v_lshlrev_b64 v[8:9], 11, v[28:29]
	v_lshl_add_u64 v[42:43], v[18:19], 0, v[8:9]
	v_lshlrev_b64 v[8:9], 9, v[28:29]
	v_lshl_add_u64 v[10:11], v[14:15], 0, v[8:9]
	v_lshl_add_u64 v[8:9], v[12:13], 0, v[8:9]
	global_load_dwordx2 v[44:45], v[42:43], off offset:1536
	s_nop 0
	global_load_dwordx2 v[10:11], v[10:11], off
	s_waitcnt vmcnt(1)
	v_lshlrev_b32_e32 v58, 16, v45
	global_load_dwordx2 v[8:9], v[8:9], off
	s_waitcnt vmcnt(1)
	v_and_b32_e32 v47, 0xffff0000, v11
	v_lshlrev_b32_e32 v46, 16, v11
	v_and_b32_e32 v49, 0xffff0000, v10
	v_lshlrev_b32_e32 v48, 16, v10
	v_and_b32_e32 v59, 0xffff0000, v45
	v_mov_b32_e32 v45, v59
	s_waitcnt vmcnt(0)
	v_and_b32_e32 v11, 0xffff0000, v9
	v_lshlrev_b32_e32 v10, 16, v9
	v_pk_fma_f32 v[10:11], v[6:7], v[46:47], v[10:11]
	v_lshlrev_b32_e32 v46, 16, v44
	v_mul_f32_e32 v29, 0x3d372713, v46
	v_and_b32_e32 v47, 0xffff0000, v44
	v_mul_f32_e32 v29, v29, v46
	v_mov_b32_e32 v44, v46
	v_fmac_f32_e32 v44, v29, v44
	v_mul_f32_e32 v29, 0xbfcc422a, v44
	v_mul_f32_e32 v29, 0x3fb8aa3b, v29
	v_exp_f32_e32 v29, v29
	v_and_b32_e32 v9, 0xffff0000, v8
	v_lshlrev_b32_e32 v8, 16, v8
	v_pk_fma_f32 v[8:9], v[4:5], v[48:49], v[8:9]
	v_add_f32_e32 v29, 1.0, v29
	v_rcp_f32_e32 v48, v29
	v_mul_f32_e32 v29, 0x3d372713, v47
	v_mul_f32_e32 v29, v29, v47
	v_mov_b32_e32 v44, v47
	v_fmac_f32_e32 v44, v29, v44
	v_mul_f32_e32 v29, 0xbfcc422a, v44
	v_mul_f32_e32 v29, 0x3fb8aa3b, v29
	v_exp_f32_e32 v29, v29
	v_mov_b32_e32 v44, v58
	v_add_f32_e32 v29, 1.0, v29
	v_rcp_f32_e32 v49, v29
	v_mul_f32_e32 v29, 0x3d372713, v58
	v_mul_f32_e32 v29, v29, v58
	v_fmac_f32_e32 v44, v29, v44
	v_mul_f32_e32 v29, 0xbfcc422a, v44
	v_mul_f32_e32 v29, 0x3fb8aa3b, v29
	v_exp_f32_e32 v29, v29
	v_pk_mul_f32 v[46:47], v[48:49], v[46:47]
	v_add_f32_e32 v29, 1.0, v29
	v_rcp_f32_e32 v44, v29
	v_mul_f32_e32 v29, 0x3d372713, v59
	v_mul_f32_e32 v29, v29, v59
	v_fmac_f32_e32 v45, v29, v45
	v_mul_f32_e32 v29, 0xbfcc422a, v45
	v_mul_f32_e32 v29, 0x3fb8aa3b, v29
	v_exp_f32_e32 v29, v29
	v_pk_mul_f32 v[46:47], v[8:9], v[46:47]
	v_add_f32_e32 v29, 1.0, v29
	v_rcp_f32_e32 v45, v29
	v_pk_mul_f32 v[48:49], v[46:47], v[46:47]
	v_pk_mul_f32 v[44:45], v[44:45], v[58:59]
	s_nop 0
	v_pk_mul_f32 v[44:45], v[10:11], v[44:45]
	v_add_f32_e32 v29, v48, v49
	v_pk_mul_f32 v[58:59], v[44:45], v[44:45]
	s_nop 0
	v_add_f32_e32 v29, v58, v29
	v_add_f32_e32 v29, v59, v29
	s_nop 1
	v_mov_b32_dpp v48, v29 quad_perm:[1,0,3,2] row_mask:0xf bank_mask:0xf

	v_add_f32_e32 v29, v29, v48
	s_nop 1
	v_mov_b32_dpp v48, v29 quad_perm:[2,3,0,1] row_mask:0xf bank_mask:0xf

	v_add_f32_e32 v29, v29, v48
	s_nop 1
	v_mov_b32_dpp v48, v29 row_half_mirror row_mask:0xf bank_mask:0xf

	v_add_f32_e32 v29, v29, v48
	s_nop 1
	v_mov_b32_dpp v48, v29 row_mirror row_mask:0xf bank_mask:0xf

	v_add_f32_e32 v29, v29, v48
	ds_bpermute_b32 v48, v54, v29
	s_waitcnt lgkmcnt(0)
	v_add_f32_e32 v29, v29, v48
	ds_bpermute_b32 v48, v55, v29
	s_waitcnt lgkmcnt(0)
	v_add_f32_e32 v29, v29, v48
	v_fmamk_f32 v29, v29, 0x3b800000, v191
	v_cmp_gt_f32_e64 s[44:45], s77, v29
	v_mul_f32_e32 v48, 0x4b800000, v29
	s_nop 0
	v_cndmask_b32_e64 v29, v29, v48, s[44:45]
	v_rsq_f32_e32 v29, v29
	s_nop 0
	v_mul_f32_e32 v48, 0x45800000, v29
	v_cndmask_b32_e64 v29, v29, v48, s[44:45]
	v_cmp_eq_u32_e64 s[44:45], s14, v56
	v_mul_f32_e32 v46, v46, v29
	v_mul_f32_e32 v47, v47, v29
	s_and_b64 s[16:17], s[46:47], s[44:45]
	v_cvt_pk_bf16_f32 v46, v46, v47
	v_mul_f32_e32 v44, v44, v29
	v_mul_f32_e32 v29, v45, v29
	v_cvt_pk_bf16_f32 v47, v44, v29
	global_store_dwordx2 v[42:43], v[46:47], off offset:1536
	s_and_saveexec_b64 s[10:11], s[16:17]
	s_cbranch_execz .LBB0_349
	global_store_dwordx4 v[16:17], v[8:11], off
.LBB0_349:
	s_or_b64 exec, exec, s[10:11]
	s_and_saveexec_b64 s[10:11], s[42:43]
	s_cbranch_execz .LBB0_352
	v_lshlrev_b32_e32 v8, 16, v40
	v_and_b32_e32 v9, 0xffff0000, v40
	v_lshlrev_b32_e32 v10, 16, v41
	v_and_b32_e32 v11, 0xffff0000, v41
	v_lshlrev_b32_e32 v40, 16, v38
	v_and_b32_e32 v41, 0xffff0000, v38
	v_lshlrev_b32_e32 v38, 16, v39
	v_and_b32_e32 v39, 0xffff0000, v39
	v_pk_fma_f32 v[10:11], v[6:7], v[38:39], v[10:11]
	v_lshlrev_b32_e32 v38, 16, v36
	v_mul_f32_e32 v29, 0x3d372713, v38
	v_and_b32_e32 v39, 0xffff0000, v36
	v_mul_f32_e32 v29, v29, v38
	v_mov_b32_e32 v36, v38
	v_fmac_f32_e32 v36, v29, v36
	v_mul_f32_e32 v29, 0xbfcc422a, v36
	v_mul_f32_e32 v36, 0x3d372713, v39
	v_mul_f32_e32 v36, v36, v39
	v_mov_b32_e32 v42, v39
	v_fmac_f32_e32 v42, v36, v42
	v_mul_f32_e32 v29, 0x3fb8aa3b, v29
	v_mul_f32_e32 v36, 0xbfcc422a, v42
	v_exp_f32_e32 v29, v29
	v_mul_f32_e32 v36, 0x3fb8aa3b, v36
	v_exp_f32_e32 v42, v36
	v_pk_fma_f32 v[8:9], v[4:5], v[40:41], v[8:9]
	v_lshlrev_b32_e32 v40, 16, v37
	v_add_f32_e32 v29, 1.0, v29
	v_and_b32_e32 v41, 0xffff0000, v37
	v_mul_f32_e32 v37, 0x3d372713, v40
	v_rcp_f32_e32 v36, v29
	v_add_f32_e32 v29, 1.0, v42
	v_mul_f32_e32 v37, v37, v40
	v_mov_b32_e32 v42, v40
	v_fmac_f32_e32 v42, v37, v42
	v_mul_f32_e32 v37, 0xbfcc422a, v42
	v_mul_f32_e32 v37, 0x3fb8aa3b, v37
	v_exp_f32_e32 v42, v37
	v_mul_f32_e32 v37, 0x3d372713, v41
	v_mul_f32_e32 v37, v37, v41
	v_mov_b32_e32 v43, v41
	v_fmac_f32_e32 v43, v37, v43
	v_mul_f32_e32 v37, 0xbfcc422a, v43
	v_mul_f32_e32 v37, 0x3fb8aa3b, v37
	v_exp_f32_e32 v43, v37
	v_rcp_f32_e32 v37, v29
	v_add_f32_e32 v29, 1.0, v42
	v_rcp_f32_e32 v42, v29
	v_add_f32_e32 v29, 1.0, v43
	v_rcp_f32_e32 v43, v29
	v_pk_mul_f32 v[36:37], v[36:37], v[38:39]
	v_pk_mul_f32 v[40:41], v[42:43], v[40:41]
	v_pk_mul_f32 v[36:37], v[8:9], v[36:37]
	v_pk_mul_f32 v[40:41], v[10:11], v[40:41]
	v_pk_mul_f32 v[38:39], v[36:37], v[36:37]
	v_pk_mul_f32 v[42:43], v[40:41], v[40:41]
	v_add_f32_e32 v29, v38, v39
	v_add_f32_e32 v29, v42, v29
	v_add_f32_e32 v29, v43, v29
	s_nop 1
	v_mov_b32_dpp v38, v29 quad_perm:[1,0,3,2] row_mask:0xf bank_mask:0xf

	v_add_f32_e32 v29, v29, v38
	s_nop 1
	v_mov_b32_dpp v38, v29 quad_perm:[2,3,0,1] row_mask:0xf bank_mask:0xf

	v_add_f32_e32 v29, v29, v38
	s_nop 1
	v_mov_b32_dpp v38, v29 row_half_mirror row_mask:0xf bank_mask:0xf

	v_add_f32_e32 v29, v29, v38
	s_nop 1
	v_mov_b32_dpp v38, v29 row_mirror row_mask:0xf bank_mask:0xf

	v_add_f32_e32 v29, v29, v38
	ds_bpermute_b32 v38, v54, v29
	s_waitcnt lgkmcnt(0)
	v_add_f32_e32 v29, v29, v38
	ds_bpermute_b32 v38, v55, v29
	s_waitcnt lgkmcnt(0)
	v_add_f32_e32 v29, v29, v38
	v_fmamk_f32 v29, v29, 0x3b800000, v191
	v_mul_f32_e32 v38, 0x4b800000, v29
	v_cmp_gt_f32_e64 s[42:43], s77, v29
	s_nop 1
	v_cndmask_b32_e64 v29, v29, v38, s[42:43]
	v_rsq_f32_e32 v29, v29
	v_add_u32_e32 v38, 8, v28
	v_ashrrev_i32_e32 v39, 31, v38
	v_lshlrev_b64 v[38:39], 11, v[38:39]
	v_mul_f32_e32 v42, 0x45800000, v29
	v_cndmask_b32_e64 v29, v29, v42, s[42:43]
	v_mul_f32_e32 v36, v36, v29
	v_mul_f32_e32 v37, v37, v29
	v_cmp_eq_u32_e64 s[42:43], s30, v56
	v_cvt_pk_bf16_f32 v36, v36, v37
	v_mul_f32_e32 v37, v40, v29
	v_lshl_add_u64 v[38:39], v[18:19], 0, v[38:39]
	s_and_b64 s[16:17], s[46:47], s[42:43]
	v_mul_f32_e32 v29, v41, v29
	v_cvt_pk_bf16_f32 v37, v37, v29
	global_store_dwordx2 v[38:39], v[36:37], off offset:1536
	s_and_b64 exec, exec, s[16:17]
	s_cbranch_execz .LBB0_352
	global_store_dwordx4 v[16:17], v[8:11], off
.LBB0_352:
	s_or_b64 exec, exec, s[10:11]
	s_and_saveexec_b64 s[10:11], s[40:41]
	s_cbranch_execz .LBB0_355
	v_lshlrev_b32_e32 v8, 16, v34
	v_and_b32_e32 v9, 0xffff0000, v34
	v_lshlrev_b32_e32 v10, 16, v35
	v_and_b32_e32 v11, 0xffff0000, v35
	v_lshlrev_b32_e32 v34, 16, v32
	v_and_b32_e32 v35, 0xffff0000, v32
	v_lshlrev_b32_e32 v32, 16, v33
	v_and_b32_e32 v33, 0xffff0000, v33
	v_pk_fma_f32 v[10:11], v[6:7], v[32:33], v[10:11]
	v_lshlrev_b32_e32 v32, 16, v30
	v_mul_f32_e32 v29, 0x3d372713, v32
	v_and_b32_e32 v33, 0xffff0000, v30
	v_mul_f32_e32 v29, v29, v32
	v_mov_b32_e32 v30, v32
	v_fmac_f32_e32 v30, v29, v30
	v_mul_f32_e32 v29, 0xbfcc422a, v30
	v_mul_f32_e32 v30, 0x3d372713, v33
	v_mul_f32_e32 v30, v30, v33
	v_mov_b32_e32 v36, v33
	v_fmac_f32_e32 v36, v30, v36
	v_mul_f32_e32 v29, 0x3fb8aa3b, v29
	v_mul_f32_e32 v30, 0xbfcc422a, v36
	v_exp_f32_e32 v29, v29
	v_mul_f32_e32 v30, 0x3fb8aa3b, v30
	v_exp_f32_e32 v36, v30
	v_pk_fma_f32 v[8:9], v[4:5], v[34:35], v[8:9]
	v_lshlrev_b32_e32 v34, 16, v31
	v_add_f32_e32 v29, 1.0, v29
	v_and_b32_e32 v35, 0xffff0000, v31
	v_mul_f32_e32 v31, 0x3d372713, v34
	v_rcp_f32_e32 v30, v29
	v_add_f32_e32 v29, 1.0, v36
	v_mul_f32_e32 v31, v31, v34
	v_mov_b32_e32 v36, v34
	v_fmac_f32_e32 v36, v31, v36
	v_mul_f32_e32 v31, 0xbfcc422a, v36
	v_mul_f32_e32 v31, 0x3fb8aa3b, v31
	v_exp_f32_e32 v36, v31
	v_mul_f32_e32 v31, 0x3d372713, v35
	v_mul_f32_e32 v31, v31, v35
	v_mov_b32_e32 v37, v35
	v_fmac_f32_e32 v37, v31, v37
	v_mul_f32_e32 v31, 0xbfcc422a, v37
	v_mul_f32_e32 v31, 0x3fb8aa3b, v31
	v_exp_f32_e32 v37, v31
	v_rcp_f32_e32 v31, v29
	v_add_f32_e32 v29, 1.0, v36
	v_rcp_f32_e32 v36, v29
	v_add_f32_e32 v29, 1.0, v37
	v_rcp_f32_e32 v37, v29
	v_pk_mul_f32 v[30:31], v[30:31], v[32:33]
	v_pk_mul_f32 v[34:35], v[36:37], v[34:35]
	v_pk_mul_f32 v[30:31], v[8:9], v[30:31]
	v_pk_mul_f32 v[34:35], v[10:11], v[34:35]
	v_pk_mul_f32 v[32:33], v[30:31], v[30:31]
	v_pk_mul_f32 v[36:37], v[34:35], v[34:35]
	v_add_f32_e32 v29, v32, v33
	v_add_f32_e32 v29, v36, v29
	v_add_f32_e32 v29, v37, v29
	s_nop 1
	v_mov_b32_dpp v32, v29 quad_perm:[1,0,3,2] row_mask:0xf bank_mask:0xf

	v_add_f32_e32 v29, v29, v32
	s_nop 1
	v_mov_b32_dpp v32, v29 quad_perm:[2,3,0,1] row_mask:0xf bank_mask:0xf

	v_add_f32_e32 v29, v29, v32
	s_nop 1
	v_mov_b32_dpp v32, v29 row_half_mirror row_mask:0xf bank_mask:0xf

	v_add_f32_e32 v29, v29, v32
	s_nop 1
	v_mov_b32_dpp v32, v29 row_mirror row_mask:0xf bank_mask:0xf

	v_add_f32_e32 v29, v29, v32
	ds_bpermute_b32 v32, v54, v29
	s_waitcnt lgkmcnt(0)
	v_add_f32_e32 v29, v29, v32
	ds_bpermute_b32 v32, v55, v29
	s_waitcnt lgkmcnt(0)
	v_add_f32_e32 v29, v29, v32
	v_fmamk_f32 v29, v29, 0x3b800000, v191
	v_mul_f32_e32 v32, 0x4b800000, v29
	v_cmp_gt_f32_e64 s[40:41], s77, v29
	s_nop 1
	v_cndmask_b32_e64 v29, v29, v32, s[40:41]
	v_rsq_f32_e32 v29, v29
	v_add_u32_e32 v32, 16, v28
	v_ashrrev_i32_e32 v33, 31, v32
	v_lshlrev_b64 v[32:33], 11, v[32:33]
	v_mul_f32_e32 v36, 0x45800000, v29
	v_cndmask_b32_e64 v29, v29, v36, s[40:41]
	v_mul_f32_e32 v30, v30, v29
	v_mul_f32_e32 v31, v31, v29
	v_cmp_eq_u32_e64 s[40:41], s29, v56
	v_cvt_pk_bf16_f32 v30, v30, v31
	v_mul_f32_e32 v31, v34, v29
	v_lshl_add_u64 v[32:33], v[18:19], 0, v[32:33]
	s_and_b64 s[16:17], s[46:47], s[40:41]
	v_mul_f32_e32 v29, v35, v29
	v_cvt_pk_bf16_f32 v31, v31, v29
	global_store_dwordx2 v[32:33], v[30:31], off offset:1536
	s_and_b64 exec, exec, s[16:17]
	s_cbranch_execz .LBB0_355
	global_store_dwordx4 v[16:17], v[8:11], off
.LBB0_355:
	s_or_b64 exec, exec, s[10:11]
	s_and_saveexec_b64 s[10:11], vcc
	s_cbranch_execz .LBB0_346
	v_lshlrev_b32_e32 v8, 16, v26
	v_and_b32_e32 v9, 0xffff0000, v26
	v_lshlrev_b32_e32 v10, 16, v27
	v_and_b32_e32 v11, 0xffff0000, v27
	v_lshlrev_b32_e32 v26, 16, v24
	v_and_b32_e32 v27, 0xffff0000, v24
	v_lshlrev_b32_e32 v24, 16, v25
	v_and_b32_e32 v25, 0xffff0000, v25
	v_pk_fma_f32 v[10:11], v[6:7], v[24:25], v[10:11]
	v_lshlrev_b32_e32 v24, 16, v22
	v_and_b32_e32 v25, 0xffff0000, v22
	v_mul_f32_e32 v22, 0x3d372713, v24
	v_mul_f32_e32 v22, v22, v24
	v_mov_b32_e32 v29, v24
	v_fmac_f32_e32 v29, v22, v29
	v_mul_f32_e32 v22, 0xbfcc422a, v29
	v_mul_f32_e32 v29, 0x3d372713, v25
	v_mul_f32_e32 v29, v29, v25
	v_mov_b32_e32 v30, v25
	v_pk_fma_f32 v[8:9], v[4:5], v[26:27], v[8:9]
	v_lshlrev_b32_e32 v26, 16, v23
	v_fmac_f32_e32 v30, v29, v30
	v_and_b32_e32 v27, 0xffff0000, v23
	v_mul_f32_e32 v23, 0x3d372713, v26
	v_mul_f32_e32 v29, 0xbfcc422a, v30
	v_mul_f32_e32 v23, v23, v26
	v_mov_b32_e32 v30, v26
	v_fmac_f32_e32 v30, v23, v30
	v_mul_f32_e32 v23, 0xbfcc422a, v30
	v_mul_f32_e32 v23, 0x3fb8aa3b, v23
	v_exp_f32_e32 v30, v23
	v_mul_f32_e32 v23, 0x3d372713, v27
	v_mul_f32_e32 v23, v23, v27
	v_mov_b32_e32 v31, v27
	v_mul_f32_e32 v29, 0x3fb8aa3b, v29
	v_fmac_f32_e32 v31, v23, v31
	v_mul_f32_e32 v22, 0x3fb8aa3b, v22
	v_exp_f32_e32 v29, v29
	v_mul_f32_e32 v23, 0xbfcc422a, v31
	v_exp_f32_e32 v22, v22
	v_mul_f32_e32 v23, 0x3fb8aa3b, v23
	v_exp_f32_e32 v31, v23
	v_add_f32_e32 v29, 1.0, v29
	v_add_f32_e32 v22, 1.0, v22
	v_rcp_f32_e32 v23, v29
	v_add_f32_e32 v29, 1.0, v30
	v_rcp_f32_e32 v22, v22
	v_rcp_f32_e32 v30, v29
	v_add_f32_e32 v29, 1.0, v31
	v_rcp_f32_e32 v31, v29
	v_pk_mul_f32 v[22:23], v[22:23], v[24:25]
	v_pk_mul_f32 v[26:27], v[30:31], v[26:27]
	v_pk_mul_f32 v[22:23], v[8:9], v[22:23]
	v_pk_mul_f32 v[26:27], v[10:11], v[26:27]
	v_pk_mul_f32 v[24:25], v[22:23], v[22:23]
	v_pk_mul_f32 v[30:31], v[26:27], v[26:27]
	v_add_f32_e32 v24, v24, v25
	v_add_f32_e32 v24, v30, v24
	v_add_f32_e32 v24, v31, v24
	s_nop 1
	v_mov_b32_dpp v25, v24 quad_perm:[1,0,3,2] row_mask:0xf bank_mask:0xf

	v_add_f32_e32 v24, v24, v25
	s_nop 1
	v_mov_b32_dpp v25, v24 quad_perm:[2,3,0,1] row_mask:0xf bank_mask:0xf

	v_add_f32_e32 v24, v24, v25
	s_nop 1
	v_mov_b32_dpp v25, v24 row_half_mirror row_mask:0xf bank_mask:0xf

	v_add_f32_e32 v24, v24, v25
	s_nop 1
	v_mov_b32_dpp v25, v24 row_mirror row_mask:0xf bank_mask:0xf

	v_add_f32_e32 v24, v24, v25
	ds_bpermute_b32 v25, v54, v24
	s_waitcnt lgkmcnt(0)
	v_add_f32_e32 v24, v24, v25
	ds_bpermute_b32 v25, v55, v24
	s_waitcnt lgkmcnt(0)
	v_add_f32_e32 v24, v24, v25
	v_fmamk_f32 v24, v24, 0x3b800000, v191
	v_mul_f32_e32 v25, 0x4b800000, v24
	v_cmp_gt_f32_e32 vcc, s77, v24
	s_nop 1
	v_cndmask_b32_e32 v24, v24, v25, vcc
	v_rsq_f32_e32 v29, v24
	v_add_u32_e32 v24, 24, v28
	v_ashrrev_i32_e32 v25, 31, v24
	v_lshlrev_b64 v[24:25], 11, v[24:25]
	v_mul_f32_e32 v28, 0x45800000, v29
	v_cndmask_b32_e32 v28, v29, v28, vcc
	v_mul_f32_e32 v22, v22, v28
	v_mul_f32_e32 v23, v23, v28
	v_cmp_eq_u32_e32 vcc, s24, v56
	v_cvt_pk_bf16_f32 v22, v22, v23
	v_mul_f32_e32 v23, v26, v28
	v_lshl_add_u64 v[24:25], v[18:19], 0, v[24:25]
	s_and_b64 s[16:17], s[46:47], vcc
	v_mul_f32_e32 v26, v27, v28
	v_cvt_pk_bf16_f32 v23, v23, v26
	global_store_dwordx2 v[24:25], v[22:23], off offset:1536
	s_and_b64 exec, exec, s[16:17]
	s_cbranch_execz .LBB0_346
	global_store_dwordx4 v[16:17], v[8:11], off
	s_branch .LBB0_346

.LBB0_472:
	v_add_u32_e32 v8, 8, v52
	v_cmp_gt_i32_e64 s[42:43], s13, v8
	v_add_u32_e32 v28, s15, v52
	v_ashrrev_i32_e32 v29, 31, v28
	v_cndmask_b32_e64 v8, v52, v8, s[42:43]
	v_add_u32_e32 v8, s15, v8
	v_ashrrev_i32_e32 v9, 31, v8
	v_lshlrev_b64 v[10:11], 9, v[8:9]
	v_lshlrev_b64 v[8:9], 11, v[8:9]
	v_lshl_add_u64 v[22:23], v[12:13], 0, v[10:11]
	v_lshl_add_u64 v[10:11], v[14:15], 0, v[10:11]
	v_lshl_add_u64 v[8:9], v[18:19], 0, v[8:9]
	global_load_dwordx2 v[40:41], v[22:23], off
	global_load_dwordx2 v[38:39], v[10:11], off
	global_load_dwordx2 v[36:37], v[8:9], off offset:1536
	v_add_u32_e32 v8, 16, v52
	v_cmp_gt_i32_e64 s[40:41], s13, v8
	s_nop 1
	v_cndmask_b32_e64 v8, v52, v8, s[40:41]
	v_add_u32_e32 v8, s15, v8
	v_ashrrev_i32_e32 v9, 31, v8
	v_lshlrev_b64 v[10:11], 9, v[8:9]
	v_lshlrev_b64 v[8:9], 11, v[8:9]
	v_lshl_add_u64 v[22:23], v[12:13], 0, v[10:11]
	v_lshl_add_u64 v[10:11], v[14:15], 0, v[10:11]
	v_lshl_add_u64 v[8:9], v[18:19], 0, v[8:9]
	global_load_dwordx2 v[34:35], v[22:23], off
	global_load_dwordx2 v[32:33], v[10:11], off
	global_load_dwordx2 v[30:31], v[8:9], off offset:1536
	v_add_u32_e32 v8, 24, v52
	v_cmp_gt_i32_e32 vcc, s13, v8
	s_nop 1
	v_cndmask_b32_e32 v8, v52, v8, vcc
	v_add_u32_e32 v8, s15, v8
	v_ashrrev_i32_e32 v9, 31, v8
	v_lshlrev_b64 v[10:11], 9, v[8:9]
	v_lshlrev_b64 v[8:9], 11, v[8:9]
	v_lshl_add_u64 v[22:23], v[12:13], 0, v[10:11]
	v_lshl_add_u64 v[10:11], v[14:15], 0, v[10:11]
	v_lshl_add_u64 v[8:9], v[18:19], 0, v[8:9]
	global_load_dwordx2 v[26:27], v[22:23], off
	global_load_dwordx2 v[24:25], v[10:11], off
	s_nop 0
	global_load_dwordx2 v[22:23], v[8:9], off offset:1536
	v_lshlrev_b64 v[8:9], 11, v[28:29]
	v_lshl_add_u64 v[42:43], v[18:19], 0, v[8:9]
	v_lshlrev_b64 v[8:9], 9, v[28:29]
	v_lshl_add_u64 v[10:11], v[14:15], 0, v[8:9]
	v_lshl_add_u64 v[8:9], v[12:13], 0, v[8:9]
	global_load_dwordx2 v[44:45], v[42:43], off offset:1536
	s_nop 0
	global_load_dwordx2 v[10:11], v[10:11], off
	s_waitcnt vmcnt(1)
	v_lshlrev_b32_e32 v54, 16, v45
	global_load_dwordx2 v[8:9], v[8:9], off
	s_waitcnt vmcnt(1)
	v_and_b32_e32 v47, 0xffff0000, v11
	v_lshlrev_b32_e32 v46, 16, v11
	v_and_b32_e32 v49, 0xffff0000, v10
	v_lshlrev_b32_e32 v48, 16, v10
	v_and_b32_e32 v55, 0xffff0000, v45
	v_mov_b32_e32 v45, v55
	s_waitcnt vmcnt(0)
	v_and_b32_e32 v11, 0xffff0000, v9
	v_lshlrev_b32_e32 v10, 16, v9
	v_pk_fma_f32 v[10:11], v[6:7], v[46:47], v[10:11]
	v_lshlrev_b32_e32 v46, 16, v44
	v_mul_f32_e32 v29, 0x3d372713, v46
	v_and_b32_e32 v47, 0xffff0000, v44
	v_mul_f32_e32 v29, v29, v46
	v_mov_b32_e32 v44, v46
	v_fmac_f32_e32 v44, v29, v44
	v_mul_f32_e32 v29, 0xbfcc422a, v44
	v_mul_f32_e32 v29, 0x3fb8aa3b, v29
	v_exp_f32_e32 v29, v29
	v_and_b32_e32 v9, 0xffff0000, v8
	v_lshlrev_b32_e32 v8, 16, v8
	v_pk_fma_f32 v[8:9], v[4:5], v[48:49], v[8:9]
	v_add_f32_e32 v29, 1.0, v29
	v_rcp_f32_e32 v48, v29
	v_mul_f32_e32 v29, 0x3d372713, v47
	v_mul_f32_e32 v29, v29, v47
	v_mov_b32_e32 v44, v47
	v_fmac_f32_e32 v44, v29, v44
	v_mul_f32_e32 v29, 0xbfcc422a, v44
	v_mul_f32_e32 v29, 0x3fb8aa3b, v29
	v_exp_f32_e32 v29, v29
	v_mov_b32_e32 v44, v54
	v_add_f32_e32 v29, 1.0, v29
	v_rcp_f32_e32 v49, v29
	v_mul_f32_e32 v29, 0x3d372713, v54
	v_mul_f32_e32 v29, v29, v54
	v_fmac_f32_e32 v44, v29, v44
	v_mul_f32_e32 v29, 0xbfcc422a, v44
	v_mul_f32_e32 v29, 0x3fb8aa3b, v29
	v_exp_f32_e32 v29, v29
	v_pk_mul_f32 v[46:47], v[48:49], v[46:47]
	v_add_f32_e32 v29, 1.0, v29
	v_rcp_f32_e32 v44, v29
	v_mul_f32_e32 v29, 0x3d372713, v55
	v_mul_f32_e32 v29, v29, v55
	v_fmac_f32_e32 v45, v29, v45
	v_mul_f32_e32 v29, 0xbfcc422a, v45
	v_mul_f32_e32 v29, 0x3fb8aa3b, v29
	v_exp_f32_e32 v29, v29
	v_pk_mul_f32 v[46:47], v[8:9], v[46:47]
	v_add_f32_e32 v29, 1.0, v29
	v_rcp_f32_e32 v45, v29
	v_pk_mul_f32 v[48:49], v[46:47], v[46:47]
	v_pk_mul_f32 v[44:45], v[44:45], v[54:55]
	s_nop 0
	v_pk_mul_f32 v[44:45], v[10:11], v[44:45]
	v_add_f32_e32 v29, v48, v49
	v_pk_mul_f32 v[54:55], v[44:45], v[44:45]
	s_nop 0
	v_add_f32_e32 v29, v54, v29
	v_add_f32_e32 v29, v55, v29
	s_nop 1
	v_mov_b32_dpp v48, v29 quad_perm:[1,0,3,2] row_mask:0xf bank_mask:0xf

	v_add_f32_e32 v29, v29, v48
	s_nop 1
	v_mov_b32_dpp v48, v29 quad_perm:[2,3,0,1] row_mask:0xf bank_mask:0xf

	v_add_f32_e32 v29, v29, v48
	s_nop 1
	v_mov_b32_dpp v48, v29 row_half_mirror row_mask:0xf bank_mask:0xf

	v_add_f32_e32 v29, v29, v48
	s_nop 1
	v_mov_b32_dpp v48, v29 row_mirror row_mask:0xf bank_mask:0xf

	v_add_f32_e32 v29, v29, v48
	ds_bpermute_b32 v48, v50, v29
	s_waitcnt lgkmcnt(0)
	v_add_f32_e32 v29, v29, v48
	ds_bpermute_b32 v48, v51, v29
	s_waitcnt lgkmcnt(0)
	v_add_f32_e32 v29, v29, v48
	v_fmamk_f32 v29, v29, 0x3b800000, v191
	v_cmp_gt_f32_e64 s[44:45], s77, v29
	v_mul_f32_e32 v48, 0x4b800000, v29
	s_nop 0
	v_cndmask_b32_e64 v29, v29, v48, s[44:45]
	v_rsq_f32_e32 v29, v29
	s_nop 0
	v_mul_f32_e32 v48, 0x45800000, v29
	v_cndmask_b32_e64 v29, v29, v48, s[44:45]
	v_cmp_eq_u32_e64 s[44:45], s24, v52
	v_mul_f32_e32 v46, v46, v29
	v_mul_f32_e32 v47, v47, v29
	s_and_b64 s[16:17], s[46:47], s[44:45]
	v_cvt_pk_bf16_f32 v46, v46, v47
	v_mul_f32_e32 v44, v44, v29
	v_mul_f32_e32 v29, v45, v29
	v_cvt_pk_bf16_f32 v47, v44, v29
	global_store_dwordx2 v[42:43], v[46:47], off offset:1536
	s_and_saveexec_b64 s[10:11], s[16:17]
	s_cbranch_execz .LBB0_474
	global_store_dwordx4 v[16:17], v[8:11], off
.LBB0_474:
	s_or_b64 exec, exec, s[10:11]
	s_and_saveexec_b64 s[10:11], s[42:43]
	s_cbranch_execz .LBB0_477
	v_lshlrev_b32_e32 v8, 16, v40
	v_and_b32_e32 v9, 0xffff0000, v40
	v_lshlrev_b32_e32 v10, 16, v41
	v_and_b32_e32 v11, 0xffff0000, v41
	v_lshlrev_b32_e32 v40, 16, v38
	v_and_b32_e32 v41, 0xffff0000, v38
	v_lshlrev_b32_e32 v38, 16, v39
	v_and_b32_e32 v39, 0xffff0000, v39
	v_pk_fma_f32 v[10:11], v[6:7], v[38:39], v[10:11]
	v_lshlrev_b32_e32 v38, 16, v36
	v_mul_f32_e32 v29, 0x3d372713, v38
	v_and_b32_e32 v39, 0xffff0000, v36
	v_mul_f32_e32 v29, v29, v38
	v_mov_b32_e32 v36, v38
	v_fmac_f32_e32 v36, v29, v36
	v_mul_f32_e32 v29, 0xbfcc422a, v36
	v_mul_f32_e32 v36, 0x3d372713, v39
	v_mul_f32_e32 v36, v36, v39
	v_mov_b32_e32 v42, v39
	v_fmac_f32_e32 v42, v36, v42
	v_mul_f32_e32 v29, 0x3fb8aa3b, v29
	v_mul_f32_e32 v36, 0xbfcc422a, v42
	v_exp_f32_e32 v29, v29
	v_mul_f32_e32 v36, 0x3fb8aa3b, v36
	v_exp_f32_e32 v42, v36
	v_pk_fma_f32 v[8:9], v[4:5], v[40:41], v[8:9]
	v_lshlrev_b32_e32 v40, 16, v37
	v_add_f32_e32 v29, 1.0, v29
	v_and_b32_e32 v41, 0xffff0000, v37
	v_mul_f32_e32 v37, 0x3d372713, v40
	v_rcp_f32_e32 v36, v29
	v_add_f32_e32 v29, 1.0, v42
	v_mul_f32_e32 v37, v37, v40
	v_mov_b32_e32 v42, v40
	v_fmac_f32_e32 v42, v37, v42
	v_mul_f32_e32 v37, 0xbfcc422a, v42
	v_mul_f32_e32 v37, 0x3fb8aa3b, v37
	v_exp_f32_e32 v42, v37
	v_mul_f32_e32 v37, 0x3d372713, v41
	v_mul_f32_e32 v37, v37, v41
	v_mov_b32_e32 v43, v41
	v_fmac_f32_e32 v43, v37, v43
	v_mul_f32_e32 v37, 0xbfcc422a, v43
	v_mul_f32_e32 v37, 0x3fb8aa3b, v37
	v_exp_f32_e32 v43, v37
	v_rcp_f32_e32 v37, v29
	v_add_f32_e32 v29, 1.0, v42
	v_rcp_f32_e32 v42, v29
	v_add_f32_e32 v29, 1.0, v43
	v_rcp_f32_e32 v43, v29
	v_pk_mul_f32 v[36:37], v[36:37], v[38:39]
	v_pk_mul_f32 v[40:41], v[42:43], v[40:41]
	v_pk_mul_f32 v[36:37], v[8:9], v[36:37]
	v_pk_mul_f32 v[40:41], v[10:11], v[40:41]
	v_pk_mul_f32 v[38:39], v[36:37], v[36:37]
	v_pk_mul_f32 v[42:43], v[40:41], v[40:41]
	v_add_f32_e32 v29, v38, v39
	v_add_f32_e32 v29, v42, v29
	v_add_f32_e32 v29, v43, v29
	s_nop 1
	v_mov_b32_dpp v38, v29 quad_perm:[1,0,3,2] row_mask:0xf bank_mask:0xf

	v_add_f32_e32 v29, v29, v38
	s_nop 1
	v_mov_b32_dpp v38, v29 quad_perm:[2,3,0,1] row_mask:0xf bank_mask:0xf

	v_add_f32_e32 v29, v29, v38
	s_nop 1
	v_mov_b32_dpp v38, v29 row_half_mirror row_mask:0xf bank_mask:0xf

	v_add_f32_e32 v29, v29, v38
	s_nop 1
	v_mov_b32_dpp v38, v29 row_mirror row_mask:0xf bank_mask:0xf

	v_add_f32_e32 v29, v29, v38
	ds_bpermute_b32 v38, v50, v29
	s_waitcnt lgkmcnt(0)
	v_add_f32_e32 v29, v29, v38
	ds_bpermute_b32 v38, v51, v29
	s_waitcnt lgkmcnt(0)
	v_add_f32_e32 v29, v29, v38
	v_fmamk_f32 v29, v29, 0x3b800000, v191
	v_mul_f32_e32 v38, 0x4b800000, v29
	v_cmp_gt_f32_e64 s[42:43], s77, v29
	s_nop 1
	v_cndmask_b32_e64 v29, v29, v38, s[42:43]
	v_rsq_f32_e32 v29, v29
	v_add_u32_e32 v38, 8, v28
	v_ashrrev_i32_e32 v39, 31, v38
	v_lshlrev_b64 v[38:39], 11, v[38:39]
	v_mul_f32_e32 v42, 0x45800000, v29
	v_cndmask_b32_e64 v29, v29, v42, s[42:43]
	v_mul_f32_e32 v36, v36, v29
	v_mul_f32_e32 v37, v37, v29
	v_cmp_eq_u32_e64 s[42:43], s30, v52
	v_cvt_pk_bf16_f32 v36, v36, v37
	v_mul_f32_e32 v37, v40, v29
	v_lshl_add_u64 v[38:39], v[18:19], 0, v[38:39]
	s_and_b64 s[16:17], s[46:47], s[42:43]
	v_mul_f32_e32 v29, v41, v29
	v_cvt_pk_bf16_f32 v37, v37, v29
	global_store_dwordx2 v[38:39], v[36:37], off offset:1536
	s_and_b64 exec, exec, s[16:17]
	s_cbranch_execz .LBB0_477
	global_store_dwordx4 v[16:17], v[8:11], off
.LBB0_477:
	s_or_b64 exec, exec, s[10:11]
	s_and_saveexec_b64 s[10:11], s[40:41]
	s_cbranch_execz .LBB0_480
	v_lshlrev_b32_e32 v8, 16, v34
	v_and_b32_e32 v9, 0xffff0000, v34
	v_lshlrev_b32_e32 v10, 16, v35
	v_and_b32_e32 v11, 0xffff0000, v35
	v_lshlrev_b32_e32 v34, 16, v32
	v_and_b32_e32 v35, 0xffff0000, v32
	v_lshlrev_b32_e32 v32, 16, v33
	v_and_b32_e32 v33, 0xffff0000, v33
	v_pk_fma_f32 v[10:11], v[6:7], v[32:33], v[10:11]
	v_lshlrev_b32_e32 v32, 16, v30
	v_mul_f32_e32 v29, 0x3d372713, v32
	v_and_b32_e32 v33, 0xffff0000, v30
	v_mul_f32_e32 v29, v29, v32
	v_mov_b32_e32 v30, v32
	v_fmac_f32_e32 v30, v29, v30
	v_mul_f32_e32 v29, 0xbfcc422a, v30
	v_mul_f32_e32 v30, 0x3d372713, v33
	v_mul_f32_e32 v30, v30, v33
	v_mov_b32_e32 v36, v33
	v_fmac_f32_e32 v36, v30, v36
	v_mul_f32_e32 v29, 0x3fb8aa3b, v29
	v_mul_f32_e32 v30, 0xbfcc422a, v36
	v_exp_f32_e32 v29, v29
	v_mul_f32_e32 v30, 0x3fb8aa3b, v30
	v_exp_f32_e32 v36, v30
	v_pk_fma_f32 v[8:9], v[4:5], v[34:35], v[8:9]
	v_lshlrev_b32_e32 v34, 16, v31
	v_add_f32_e32 v29, 1.0, v29
	v_and_b32_e32 v35, 0xffff0000, v31
	v_mul_f32_e32 v31, 0x3d372713, v34
	v_rcp_f32_e32 v30, v29
	v_add_f32_e32 v29, 1.0, v36
	v_mul_f32_e32 v31, v31, v34
	v_mov_b32_e32 v36, v34
	v_fmac_f32_e32 v36, v31, v36
	v_mul_f32_e32 v31, 0xbfcc422a, v36
	v_mul_f32_e32 v31, 0x3fb8aa3b, v31
	v_exp_f32_e32 v36, v31
	v_mul_f32_e32 v31, 0x3d372713, v35
	v_mul_f32_e32 v31, v31, v35
	v_mov_b32_e32 v37, v35
	v_fmac_f32_e32 v37, v31, v37
	v_mul_f32_e32 v31, 0xbfcc422a, v37
	v_mul_f32_e32 v31, 0x3fb8aa3b, v31
	v_exp_f32_e32 v37, v31
	v_rcp_f32_e32 v31, v29
	v_add_f32_e32 v29, 1.0, v36
	v_rcp_f32_e32 v36, v29
	v_add_f32_e32 v29, 1.0, v37
	v_rcp_f32_e32 v37, v29
	v_pk_mul_f32 v[30:31], v[30:31], v[32:33]
	v_pk_mul_f32 v[34:35], v[36:37], v[34:35]
	v_pk_mul_f32 v[30:31], v[8:9], v[30:31]
	v_pk_mul_f32 v[34:35], v[10:11], v[34:35]
	v_pk_mul_f32 v[32:33], v[30:31], v[30:31]
	v_pk_mul_f32 v[36:37], v[34:35], v[34:35]
	v_add_f32_e32 v29, v32, v33
	v_add_f32_e32 v29, v36, v29
	v_add_f32_e32 v29, v37, v29
	s_nop 1
	v_mov_b32_dpp v32, v29 quad_perm:[1,0,3,2] row_mask:0xf bank_mask:0xf

	v_add_f32_e32 v29, v29, v32
	s_nop 1
	v_mov_b32_dpp v32, v29 quad_perm:[2,3,0,1] row_mask:0xf bank_mask:0xf

	v_add_f32_e32 v29, v29, v32
	s_nop 1
	v_mov_b32_dpp v32, v29 row_half_mirror row_mask:0xf bank_mask:0xf

	v_add_f32_e32 v29, v29, v32
	s_nop 1
	v_mov_b32_dpp v32, v29 row_mirror row_mask:0xf bank_mask:0xf

	v_add_f32_e32 v29, v29, v32
	ds_bpermute_b32 v32, v50, v29
	s_waitcnt lgkmcnt(0)
	v_add_f32_e32 v29, v29, v32
	ds_bpermute_b32 v32, v51, v29
	s_waitcnt lgkmcnt(0)
	v_add_f32_e32 v29, v29, v32
	v_fmamk_f32 v29, v29, 0x3b800000, v191
	v_mul_f32_e32 v32, 0x4b800000, v29
	v_cmp_gt_f32_e64 s[40:41], s77, v29
	s_nop 1
	v_cndmask_b32_e64 v29, v29, v32, s[40:41]
	v_rsq_f32_e32 v29, v29
	v_add_u32_e32 v32, 16, v28
	v_ashrrev_i32_e32 v33, 31, v32
	v_lshlrev_b64 v[32:33], 11, v[32:33]
	v_mul_f32_e32 v36, 0x45800000, v29
	v_cndmask_b32_e64 v29, v29, v36, s[40:41]
	v_mul_f32_e32 v30, v30, v29
	v_mul_f32_e32 v31, v31, v29
	v_cmp_eq_u32_e64 s[40:41], s29, v52
	v_cvt_pk_bf16_f32 v30, v30, v31
	v_mul_f32_e32 v31, v34, v29
	v_lshl_add_u64 v[32:33], v[18:19], 0, v[32:33]
	s_and_b64 s[16:17], s[46:47], s[40:41]
	v_mul_f32_e32 v29, v35, v29
	v_cvt_pk_bf16_f32 v31, v31, v29
	global_store_dwordx2 v[32:33], v[30:31], off offset:1536
	s_and_b64 exec, exec, s[16:17]
	s_cbranch_execz .LBB0_480
	global_store_dwordx4 v[16:17], v[8:11], off
.LBB0_480:
	s_or_b64 exec, exec, s[10:11]
	s_and_saveexec_b64 s[10:11], vcc
	s_cbranch_execz .LBB0_471
	v_lshlrev_b32_e32 v8, 16, v26
	v_and_b32_e32 v9, 0xffff0000, v26
	v_lshlrev_b32_e32 v10, 16, v27
	v_and_b32_e32 v11, 0xffff0000, v27
	v_lshlrev_b32_e32 v26, 16, v24
	v_and_b32_e32 v27, 0xffff0000, v24
	v_lshlrev_b32_e32 v24, 16, v25
	v_and_b32_e32 v25, 0xffff0000, v25
	v_pk_fma_f32 v[10:11], v[6:7], v[24:25], v[10:11]
	v_lshlrev_b32_e32 v24, 16, v22
	v_and_b32_e32 v25, 0xffff0000, v22
	v_mul_f32_e32 v22, 0x3d372713, v24
	v_mul_f32_e32 v22, v22, v24
	v_mov_b32_e32 v29, v24
	v_fmac_f32_e32 v29, v22, v29
	v_mul_f32_e32 v22, 0xbfcc422a, v29
	v_mul_f32_e32 v29, 0x3d372713, v25
	v_mul_f32_e32 v29, v29, v25
	v_mov_b32_e32 v30, v25
	v_pk_fma_f32 v[8:9], v[4:5], v[26:27], v[8:9]
	v_lshlrev_b32_e32 v26, 16, v23
	v_fmac_f32_e32 v30, v29, v30
	v_and_b32_e32 v27, 0xffff0000, v23
	v_mul_f32_e32 v23, 0x3d372713, v26
	v_mul_f32_e32 v29, 0xbfcc422a, v30
	v_mul_f32_e32 v23, v23, v26
	v_mov_b32_e32 v30, v26
	v_fmac_f32_e32 v30, v23, v30
	v_mul_f32_e32 v23, 0xbfcc422a, v30
	v_mul_f32_e32 v23, 0x3fb8aa3b, v23
	v_exp_f32_e32 v30, v23
	v_mul_f32_e32 v23, 0x3d372713, v27
	v_mul_f32_e32 v23, v23, v27
	v_mov_b32_e32 v31, v27
	v_mul_f32_e32 v29, 0x3fb8aa3b, v29
	v_fmac_f32_e32 v31, v23, v31
	v_mul_f32_e32 v22, 0x3fb8aa3b, v22
	v_exp_f32_e32 v29, v29
	v_mul_f32_e32 v23, 0xbfcc422a, v31
	v_exp_f32_e32 v22, v22
	v_mul_f32_e32 v23, 0x3fb8aa3b, v23
	v_exp_f32_e32 v31, v23
	v_add_f32_e32 v29, 1.0, v29
	v_add_f32_e32 v22, 1.0, v22
	v_rcp_f32_e32 v23, v29
	v_add_f32_e32 v29, 1.0, v30
	v_rcp_f32_e32 v22, v22
	v_rcp_f32_e32 v30, v29
	v_add_f32_e32 v29, 1.0, v31
	v_rcp_f32_e32 v31, v29
	v_pk_mul_f32 v[22:23], v[22:23], v[24:25]
	v_pk_mul_f32 v[26:27], v[30:31], v[26:27]
	v_pk_mul_f32 v[22:23], v[8:9], v[22:23]
	v_pk_mul_f32 v[26:27], v[10:11], v[26:27]
	v_pk_mul_f32 v[24:25], v[22:23], v[22:23]
	v_pk_mul_f32 v[30:31], v[26:27], v[26:27]
	v_add_f32_e32 v24, v24, v25
	v_add_f32_e32 v24, v30, v24
	v_add_f32_e32 v24, v31, v24
	s_nop 1
	v_mov_b32_dpp v25, v24 quad_perm:[1,0,3,2] row_mask:0xf bank_mask:0xf

	v_add_f32_e32 v24, v24, v25
	s_nop 1
	v_mov_b32_dpp v25, v24 quad_perm:[2,3,0,1] row_mask:0xf bank_mask:0xf

	v_add_f32_e32 v24, v24, v25
	s_nop 1
	v_mov_b32_dpp v25, v24 row_half_mirror row_mask:0xf bank_mask:0xf

	v_add_f32_e32 v24, v24, v25
	s_nop 1
	v_mov_b32_dpp v25, v24 row_mirror row_mask:0xf bank_mask:0xf

	v_add_f32_e32 v24, v24, v25
	ds_bpermute_b32 v25, v50, v24
	s_waitcnt lgkmcnt(0)
	v_add_f32_e32 v24, v24, v25
	ds_bpermute_b32 v25, v51, v24
	s_waitcnt lgkmcnt(0)
	v_add_f32_e32 v24, v24, v25
	v_fmamk_f32 v24, v24, 0x3b800000, v191
	v_mul_f32_e32 v25, 0x4b800000, v24
	v_cmp_gt_f32_e32 vcc, s77, v24
	s_nop 1
	v_cndmask_b32_e32 v24, v24, v25, vcc
	v_rsq_f32_e32 v29, v24
	v_add_u32_e32 v24, 24, v28
	v_ashrrev_i32_e32 v25, 31, v24
	v_lshlrev_b64 v[24:25], 11, v[24:25]
	v_mul_f32_e32 v28, 0x45800000, v29
	v_cndmask_b32_e32 v28, v29, v28, vcc
	v_mul_f32_e32 v22, v22, v28
	v_mul_f32_e32 v23, v23, v28
	v_cmp_eq_u32_e32 vcc, s28, v52
	v_cvt_pk_bf16_f32 v22, v22, v23
	v_mul_f32_e32 v23, v26, v28
	v_lshl_add_u64 v[24:25], v[18:19], 0, v[24:25]
	s_and_b64 s[16:17], s[46:47], vcc
	v_mul_f32_e32 v26, v27, v28
	v_cvt_pk_bf16_f32 v23, v23, v26
	global_store_dwordx2 v[24:25], v[22:23], off offset:1536
	s_and_b64 exec, exec, s[16:17]
	s_cbranch_execz .LBB0_471
	global_store_dwordx4 v[16:17], v[8:11], off
	s_branch .LBB0_471
